# scan phase: helper waves 4-7 do the whole next-chunk load+prep (both halves) while waves 0-3 run the MFMA compute; compute waves skip load/prep
# speedup vs baseline: 1.0224x; 1.0224x over previous
.LBB0_656:
	s_cmp_lg_u32 s65, 63
	s_cselect_b64 s[50:51], -1, 0
	s_cmp_eq_u32 s65, 63
	s_cbranch_scc1 .LBB0_670
	s_cmpk_lt_u32 s62, 0x100
	s_cbranch_scc1 .LBB0_670
	v_add_u32_e32 v21, 64, v70
	s_waitcnt vmcnt(4)
	v_subrev_u32_e32 v26, 64, v71
	s_waitcnt vmcnt(3)
	v_cndmask_b32_e64 v32, v26, v21, s[4:5]
	v_ashrrev_i32_e32 v33, 31, v32
	s_waitcnt vmcnt(1)
	v_lshl_add_u64 v[44:45], v[32:33], 0, s[40:41]
	s_waitcnt vmcnt(0)
	v_mad_u64_u32 v[46:47], s[22:23], v44, s56, v[50:51]
	v_mad_i32_i24 v47, v45, s56, v47
	global_load_dwordx2 v[26:27], v[46:47], off
	v_mov_b32_e32 v30, v20
	v_mov_b32_e32 v31, v20
	v_cmp_lt_i32_e64 s[22:23], 0, v32
	v_mov_b64_e32 v[28:29], v[30:31]
	s_and_saveexec_b64 s[24:25], s[22:23]
	s_cbranch_execz .LBB0_659
	v_add_co_u32_e32 v28, vcc, 0xfffff000, v46
	s_nop 1
	v_addc_co_u32_e32 v29, vcc, -1, v47, vcc
	global_load_dwordx2 v[28:29], v[28:29], off offset:-2048

.Lmy_ck_cE:
	s_andn2_b64 vcc, exec, s[50:51]
	s_cmpk_lt_u32 s62, 0x100
	s_cbranch_scc1 .LBB0_655
	s_cbranch_vccnz .LBB0_655
	s_waitcnt vmcnt(4)
	v_lshlrev_b32_e32 v72, 16, v28
	v_and_b32_e32 v73, 0xffff0000, v28
	v_lshlrev_b32_e32 v76, 16, v30
	v_and_b32_e32 v77, 0xffff0000, v30
	v_lshlrev_b32_e32 v74, 16, v26
	v_and_b32_e32 v75, 0xffff0000, v26
	v_pk_add_f32 v[72:73], v[72:73], v[76:77]
	s_waitcnt vmcnt(2)
	v_lshlrev_b32_e32 v78, 16, v42
	v_pk_fma_f32 v[72:73], v[72:73], 0.5, v[74:75] op_sel_hi:[1,0,1] neg_lo:[0,0,1] neg_hi:[0,0,1]
	v_and_b32_e32 v79, 0xffff0000, v42
	v_pk_fma_f32 v[72:73], v[0:1], v[72:73], v[74:75]
	v_lshlrev_b32_e32 v74, 16, v40
	v_and_b32_e32 v75, 0xffff0000, v40
	v_lshlrev_b32_e32 v76, 16, v38
	v_and_b32_e32 v77, 0xffff0000, v38
	v_pk_add_f32 v[74:75], v[74:75], v[78:79]
	s_waitcnt vmcnt(1)
	v_cvt_f32_f16_e32 v21, v44
	v_pk_fma_f32 v[74:75], v[74:75], 0.5, v[76:77] op_sel_hi:[1,0,1] neg_lo:[0,0,1] neg_hi:[0,0,1]
	v_lshlrev_b32_e32 v80, 16, v31
	v_pk_fma_f32 v[76:77], v[8:9], v[74:75], v[76:77]
	v_lshlrev_b32_e32 v74, 16, v29
	v_and_b32_e32 v75, 0xffff0000, v29
	v_and_b32_e32 v81, 0xffff0000, v31
	v_lshlrev_b32_e32 v78, 16, v27
	v_and_b32_e32 v79, 0xffff0000, v27
	v_pk_add_f32 v[74:75], v[74:75], v[80:81]
	v_cvt_f32_f16_sdwa v84, v44 dst_sel:DWORD dst_unused:UNUSED_PAD src0_sel:WORD_1
	v_pk_fma_f32 v[74:75], v[74:75], 0.5, v[78:79] op_sel_hi:[1,0,1] neg_lo:[0,0,1] neg_hi:[0,0,1]
	v_lshlrev_b32_e32 v82, 16, v43
	v_pk_fma_f32 v[74:75], v[2:3], v[74:75], v[78:79]
	v_lshlrev_b32_e32 v78, 16, v41
	v_and_b32_e32 v79, 0xffff0000, v41
	v_and_b32_e32 v83, 0xffff0000, v43
	v_cvt_f32_f16_e32 v88, v45
	v_lshlrev_b32_e32 v80, 16, v39
	v_and_b32_e32 v81, 0xffff0000, v39
	v_pk_add_f32 v[78:79], v[78:79], v[82:83]
	v_mul_f32_e32 v21, 0xbf1b4598, v21
	v_pk_fma_f32 v[78:79], v[78:79], 0.5, v[80:81] op_sel_hi:[1,0,1] neg_lo:[0,0,1] neg_hi:[0,0,1]
	v_mul_f32_e32 v21, 0x3fb8aa3b, v21
	v_cvt_f32_f16_sdwa v89, v45 dst_sel:DWORD dst_unused:UNUSED_PAD src0_sel:WORD_1
	v_pk_fma_f32 v[78:79], v[10:11], v[78:79], v[80:81]
	v_exp_f32_e32 v80, v21
	v_mul_f32_e32 v21, 0xbf1b4598, v84
	v_mul_f32_e32 v21, 0x3fb8aa3b, v21
	v_lshlrev_b32_e32 v82, 16, v34
	v_and_b32_e32 v83, 0xffff0000, v34
	v_lshlrev_b32_e32 v86, 16, v36
	v_and_b32_e32 v87, 0xffff0000, v36
	v_exp_f32_e32 v81, v21
	v_lshlrev_b32_e32 v84, 16, v32
	v_and_b32_e32 v85, 0xffff0000, v32
	v_pk_add_f32 v[82:83], v[82:83], v[86:87]
	v_mul_f32_e32 v21, 0xbf1b4598, v88
	v_pk_fma_f32 v[82:83], v[82:83], 0.5, v[84:85] op_sel_hi:[1,0,1] neg_lo:[0,0,1] neg_hi:[0,0,1]
	v_mul_f32_e32 v21, 0x3fb8aa3b, v21
	v_pk_fma_f32 v[96:97], v[4:5], v[82:83], v[84:85]
	v_exp_f32_e32 v82, v21
	v_mul_f32_e32 v21, 0xbf1b4598, v89
	v_lshlrev_b32_e32 v84, 16, v35
	v_and_b32_e32 v85, 0xffff0000, v35
	v_lshlrev_b32_e32 v88, 16, v37
	v_and_b32_e32 v89, 0xffff0000, v37
	v_lshlrev_b32_e32 v86, 16, v33
	v_and_b32_e32 v87, 0xffff0000, v33
	v_pk_add_f32 v[84:85], v[84:85], v[88:89]
	s_waitcnt vmcnt(0)
	v_cvt_f32_f16_sdwa v93, v46 dst_sel:DWORD dst_unused:UNUSED_PAD src0_sel:WORD_1
	v_pk_fma_f32 v[84:85], v[84:85], 0.5, v[86:87] op_sel_hi:[1,0,1] neg_lo:[0,0,1] neg_hi:[0,0,1]
	v_cvt_f32_f16_e32 v92, v46
	v_pk_fma_f32 v[94:95], v[6:7], v[84:85], v[86:87]
	v_pk_mul_f32 v[84:85], v[12:13], v[96:97]
	v_pk_mul_f32 v[88:89], v[14:15], v[94:95]
	v_pk_mul_f32 v[86:87], v[84:85], v[84:85]
	v_pk_mul_f32 v[90:91], v[88:89], v[88:89]
	v_add_f32_e32 v83, v86, v87
	v_add_f32_e32 v83, v90, v83
	v_add_f32_e32 v83, v91, v83
	v_cvt_f32_f16_sdwa v99, v47 dst_sel:DWORD dst_unused:UNUSED_PAD src0_sel:WORD_1
	v_cvt_f32_f16_e32 v98, v47
	v_add_f32_dpp v83, v83, v83 quad_perm:[1,0,3,2] row_mask:0xf bank_mask:0xf bound_ctrl:1
	v_mul_f32_e32 v21, 0x3fb8aa3b, v21
	s_bitcmp1_b32 s22, 0
	v_add_f32_dpp v83, v83, v83 quad_perm:[2,3,0,1] row_mask:0xf bank_mask:0xf bound_ctrl:1
	s_cselect_b32 s23, 0xc000, 0
	s_nop 0
	v_add_f32_dpp v83, v83, v83 row_half_mirror row_mask:0xf bank_mask:0xf bound_ctrl:1
	s_nop 1
	v_add_f32_dpp v83, v83, v83 row_mirror row_mask:0xf bank_mask:0xf bound_ctrl:1
	v_max_f32_e32 v83, 0x179abe15, v83
	v_rsq_f32_e32 v86, v83
	v_exp_f32_e32 v83, v21
	v_add_u32_e32 v21, s23, v67
	v_pk_mul_f32 v[90:91], v[84:85], v[86:87] op_sel_hi:[1,0]
	v_pk_mul_f32 v[100:101], v[88:89], v[86:87] op_sel_hi:[1,0]
	v_xor_b32_e32 v85, 0x80000000, v91
	v_xor_b32_e32 v84, 0x80000000, v90
	v_pk_mul_f32 v[88:89], v[90:91], v[92:93]
	v_pk_mul_f32 v[90:91], v[100:101], v[98:99]
	v_pk_add_f32 v[92:93], v[92:93], -1.0 op_sel_hi:[1,0]
	v_pk_add_f32 v[98:99], v[98:99], -1.0 op_sel_hi:[1,0]
	v_pk_fma_f32 v[92:93], v[16:17], v[92:93], 1.0 op_sel_hi:[1,1,0]
	v_pk_fma_f32 v[98:99], v[18:19], v[98:99], 1.0 op_sel_hi:[1,1,0]
	v_xor_b32_e32 v86, 0x80000000, v100
	v_xor_b32_e32 v87, 0x80000000, v101
	v_pk_mul_f32 v[94:95], v[94:95], v[98:99]
	v_pk_mul_f32 v[92:93], v[96:97], v[92:93]
	ds_write_b128 v21, v[80:83]
	ds_write_b128 v21, v[84:87] offset:8192
	ds_write_b128 v21, v[88:91] offset:16384
	ds_write_b128 v21, v[92:95] offset:24576
	ds_write_b128 v21, v[72:75] offset:32768
	ds_write_b128 v21, v[76:79] offset:40960
	v_subrev_u32_e32 v70, 16, v70
	v_add_u32_e32 v71, 16, v71
	v_add_u32_e32 v67, 0xfffff000, v67
	v_add_u32_e32 v21, 64, v70
	s_waitcnt vmcnt(4)
	v_subrev_u32_e32 v26, 64, v71
	s_waitcnt vmcnt(3)
	v_cndmask_b32_e64 v32, v26, v21, s[4:5]
	v_ashrrev_i32_e32 v33, 31, v32
	s_waitcnt vmcnt(1)
	v_lshl_add_u64 v[44:45], v[32:33], 0, s[40:41]
	s_waitcnt vmcnt(0)
	v_mad_u64_u32 v[46:47], s[96:97], v44, s56, v[50:51]
	v_mad_i32_i24 v47, v45, s56, v47
	global_load_dwordx2 v[26:27], v[46:47], off
	v_mov_b32_e32 v30, v20
	v_mov_b32_e32 v31, v20
	v_cmp_lt_i32_e64 s[96:97], 0, v32
	v_mov_b64_e32 v[28:29], v[30:31]
	s_and_saveexec_b64 s[24:25], s[96:97]
	s_cbranch_execz .Lmy_p2_659
	v_add_co_u32_e32 v28, vcc, 0xfffff000, v46
	s_nop 1
	v_addc_co_u32_e32 v29, vcc, -1, v47, vcc
	global_load_dwordx2 v[28:29], v[28:29], off offset:-2048

.Lmy_p2_661:
	s_or_b64 exec, exec, s[54:55]
	global_load_dwordx2 v[32:33], v[46:47], off offset:2048
	v_mov_b32_e32 v21, v20
	v_mov_b64_e32 v[34:35], v[20:21]
	s_and_saveexec_b64 s[54:55], s[96:97]
	s_cbranch_execz .Lmy_p2_663
	global_load_dwordx2 v[34:35], v[46:47], off offset:-4096

.Lmy_p2_665:
	s_or_b64 exec, exec, s[54:55]
	v_add_co_u32_e32 v38, vcc, 0x1000, v46
	v_mov_b32_e32 v21, v20
	s_nop 0
	v_addc_co_u32_e32 v39, vcc, 0, v47, vcc
	global_load_dwordx2 v[38:39], v[38:39], off
	v_mov_b64_e32 v[40:41], v[20:21]
	s_and_saveexec_b64 s[54:55], s[96:97]
	s_cbranch_execz .Lmy_p2_667
	global_load_dwordx2 v[40:41], v[46:47], off offset:-2048
.Lmy_p2_667:
	s_or_b64 exec, exec, s[54:55]
	v_mov_b64_e32 v[42:43], v[20:21]
	s_and_saveexec_b64 s[96:97], s[24:25]
	s_cbranch_execz .Lmy_p2_669
	v_add_co_u32_e32 v42, vcc, 0x2000, v46
	s_nop 1
	v_addc_co_u32_e32 v43, vcc, 0, v47, vcc
	global_load_dwordx2 v[42:43], v[42:43], off offset:2048
.Lmy_p2_669:
	s_or_b64 exec, exec, s[96:97]
	v_lshlrev_b64 v[44:45], 13, v[44:45]
	v_lshl_add_u64 v[44:45], v[52:53], 0, v[44:45]
	v_add_co_u32_e32 v46, vcc, 0x1000, v44
	s_nop 1
	v_addc_co_u32_e32 v47, vcc, 0, v45, vcc
	global_load_dwordx2 v[44:45], v[44:45], off
	s_nop 0
	global_load_dwordx2 v[46:47], v[46:47], off
	s_waitcnt vmcnt(0)
	v_lshlrev_b32_e32 v72, 16, v28
	v_and_b32_e32 v73, 0xffff0000, v28
	v_lshlrev_b32_e32 v76, 16, v30
	v_and_b32_e32 v77, 0xffff0000, v30
	v_lshlrev_b32_e32 v74, 16, v26
	v_and_b32_e32 v75, 0xffff0000, v26
	v_pk_add_f32 v[72:73], v[72:73], v[76:77]
	s_waitcnt vmcnt(2)
	v_lshlrev_b32_e32 v78, 16, v42
	v_pk_fma_f32 v[72:73], v[72:73], 0.5, v[74:75] op_sel_hi:[1,0,1] neg_lo:[0,0,1] neg_hi:[0,0,1]
	v_and_b32_e32 v79, 0xffff0000, v42
	v_pk_fma_f32 v[72:73], v[0:1], v[72:73], v[74:75]
	v_lshlrev_b32_e32 v74, 16, v40
	v_and_b32_e32 v75, 0xffff0000, v40
	v_lshlrev_b32_e32 v76, 16, v38
	v_and_b32_e32 v77, 0xffff0000, v38
	v_pk_add_f32 v[74:75], v[74:75], v[78:79]
	s_waitcnt vmcnt(1)
	v_cvt_f32_f16_e32 v21, v44
	v_pk_fma_f32 v[74:75], v[74:75], 0.5, v[76:77] op_sel_hi:[1,0,1] neg_lo:[0,0,1] neg_hi:[0,0,1]
	v_lshlrev_b32_e32 v80, 16, v31
	v_pk_fma_f32 v[76:77], v[8:9], v[74:75], v[76:77]
	v_lshlrev_b32_e32 v74, 16, v29
	v_and_b32_e32 v75, 0xffff0000, v29
	v_and_b32_e32 v81, 0xffff0000, v31
	v_lshlrev_b32_e32 v78, 16, v27
	v_and_b32_e32 v79, 0xffff0000, v27
	v_pk_add_f32 v[74:75], v[74:75], v[80:81]
	v_cvt_f32_f16_sdwa v84, v44 dst_sel:DWORD dst_unused:UNUSED_PAD src0_sel:WORD_1
	v_pk_fma_f32 v[74:75], v[74:75], 0.5, v[78:79] op_sel_hi:[1,0,1] neg_lo:[0,0,1] neg_hi:[0,0,1]
	v_lshlrev_b32_e32 v82, 16, v43
	v_pk_fma_f32 v[74:75], v[2:3], v[74:75], v[78:79]
	v_lshlrev_b32_e32 v78, 16, v41
	v_and_b32_e32 v79, 0xffff0000, v41
	v_and_b32_e32 v83, 0xffff0000, v43
	v_cvt_f32_f16_e32 v88, v45
	v_lshlrev_b32_e32 v80, 16, v39
	v_and_b32_e32 v81, 0xffff0000, v39
	v_pk_add_f32 v[78:79], v[78:79], v[82:83]
	v_mul_f32_e32 v21, 0xbf1b4598, v21
	v_pk_fma_f32 v[78:79], v[78:79], 0.5, v[80:81] op_sel_hi:[1,0,1] neg_lo:[0,0,1] neg_hi:[0,0,1]
	v_mul_f32_e32 v21, 0x3fb8aa3b, v21
	v_cvt_f32_f16_sdwa v89, v45 dst_sel:DWORD dst_unused:UNUSED_PAD src0_sel:WORD_1
	v_pk_fma_f32 v[78:79], v[10:11], v[78:79], v[80:81]
	v_exp_f32_e32 v80, v21
	v_mul_f32_e32 v21, 0xbf1b4598, v84
	v_mul_f32_e32 v21, 0x3fb8aa3b, v21
	v_lshlrev_b32_e32 v82, 16, v34
	v_and_b32_e32 v83, 0xffff0000, v34
	v_lshlrev_b32_e32 v86, 16, v36
	v_and_b32_e32 v87, 0xffff0000, v36
	v_exp_f32_e32 v81, v21
	v_lshlrev_b32_e32 v84, 16, v32
	v_and_b32_e32 v85, 0xffff0000, v32
	v_pk_add_f32 v[82:83], v[82:83], v[86:87]
	v_mul_f32_e32 v21, 0xbf1b4598, v88
	v_pk_fma_f32 v[82:83], v[82:83], 0.5, v[84:85] op_sel_hi:[1,0,1] neg_lo:[0,0,1] neg_hi:[0,0,1]
	v_mul_f32_e32 v21, 0x3fb8aa3b, v21
	v_pk_fma_f32 v[96:97], v[4:5], v[82:83], v[84:85]
	v_exp_f32_e32 v82, v21
	v_mul_f32_e32 v21, 0xbf1b4598, v89
	v_lshlrev_b32_e32 v84, 16, v35
	v_and_b32_e32 v85, 0xffff0000, v35
	v_lshlrev_b32_e32 v88, 16, v37
	v_and_b32_e32 v89, 0xffff0000, v37
	v_lshlrev_b32_e32 v86, 16, v33
	v_and_b32_e32 v87, 0xffff0000, v33
	v_pk_add_f32 v[84:85], v[84:85], v[88:89]
	s_waitcnt vmcnt(0)
	v_cvt_f32_f16_sdwa v93, v46 dst_sel:DWORD dst_unused:UNUSED_PAD src0_sel:WORD_1
	v_pk_fma_f32 v[84:85], v[84:85], 0.5, v[86:87] op_sel_hi:[1,0,1] neg_lo:[0,0,1] neg_hi:[0,0,1]
	v_cvt_f32_f16_e32 v92, v46
	v_pk_fma_f32 v[94:95], v[6:7], v[84:85], v[86:87]
	v_pk_mul_f32 v[84:85], v[12:13], v[96:97]
	v_pk_mul_f32 v[88:89], v[14:15], v[94:95]
	v_pk_mul_f32 v[86:87], v[84:85], v[84:85]
	v_pk_mul_f32 v[90:91], v[88:89], v[88:89]
	v_add_f32_e32 v83, v86, v87
	v_add_f32_e32 v83, v90, v83
	v_add_f32_e32 v83, v91, v83
	v_cvt_f32_f16_sdwa v99, v47 dst_sel:DWORD dst_unused:UNUSED_PAD src0_sel:WORD_1
	v_cvt_f32_f16_e32 v98, v47
	v_add_f32_dpp v83, v83, v83 quad_perm:[1,0,3,2] row_mask:0xf bank_mask:0xf bound_ctrl:1
	v_mul_f32_e32 v21, 0x3fb8aa3b, v21
	s_bitcmp1_b32 s22, 0
	v_add_f32_dpp v83, v83, v83 quad_perm:[2,3,0,1] row_mask:0xf bank_mask:0xf bound_ctrl:1
	s_cselect_b32 s23, 0xc000, 0
	s_nop 0
	v_add_f32_dpp v83, v83, v83 row_half_mirror row_mask:0xf bank_mask:0xf bound_ctrl:1
	s_nop 1
	v_add_f32_dpp v83, v83, v83 row_mirror row_mask:0xf bank_mask:0xf bound_ctrl:1
	v_max_f32_e32 v83, 0x179abe15, v83
	v_rsq_f32_e32 v86, v83
	v_exp_f32_e32 v83, v21
	v_add_u32_e32 v21, s23, v67
	v_pk_mul_f32 v[90:91], v[84:85], v[86:87] op_sel_hi:[1,0]
	v_pk_mul_f32 v[100:101], v[88:89], v[86:87] op_sel_hi:[1,0]
	v_xor_b32_e32 v85, 0x80000000, v91
	v_xor_b32_e32 v84, 0x80000000, v90
	v_pk_mul_f32 v[88:89], v[90:91], v[92:93]
	v_pk_mul_f32 v[90:91], v[100:101], v[98:99]
	v_pk_add_f32 v[92:93], v[92:93], -1.0 op_sel_hi:[1,0]
	v_pk_add_f32 v[98:99], v[98:99], -1.0 op_sel_hi:[1,0]
	v_pk_fma_f32 v[92:93], v[16:17], v[92:93], 1.0 op_sel_hi:[1,1,0]
	v_pk_fma_f32 v[98:99], v[18:19], v[98:99], 1.0 op_sel_hi:[1,1,0]
	v_xor_b32_e32 v86, 0x80000000, v100
	v_xor_b32_e32 v87, 0x80000000, v101
	v_pk_mul_f32 v[94:95], v[94:95], v[98:99]
	v_pk_mul_f32 v[92:93], v[96:97], v[92:93]
	ds_write_b128 v21, v[80:83]
	ds_write_b128 v21, v[84:87] offset:8192
	ds_write_b128 v21, v[88:91] offset:16384
	ds_write_b128 v21, v[92:95] offset:24576
	ds_write_b128 v21, v[72:75] offset:32768
	ds_write_b128 v21, v[76:79] offset:40960
	v_add_u32_e32 v70, 16, v70
	v_subrev_u32_e32 v71, 16, v71
	v_add_u32_e32 v67, 0x1000, v67
	s_branch .LBB0_655
